# P5 stage 1: (dt, decay) pair loads remapped to 4 lanes per token (16 rows x 32 B per load instead of 64 rows x 8 B); on top of widened chunk-MLP stores
# baseline (speedup 1.0000x reference)
.LBB0_850:
	v_lshrrev_b32_e32 v6, 2, v180
	v_or_b32_e32 v0, s13, v6
	v_and_b32_e32 v4, 3, v180
	v_ashrrev_i32_e32 v1, 31, v0
	v_lshlrev_b64 v[0:1], 8, v[0:1]
	v_lshlrev_b32_e32 v2, 3, v4
	v_add_u32_e32 v7, 4, v4
	v_lshl_add_u64 v[0:1], s[38:39], 0, v[0:1]
	s_lshl_b32 s0, s12, 5
	s_mov_b32 s1, s47
	v_and_b32_e32 v160, 24, v2
	v_lshlrev_b32_e32 v2, 2, v4
	v_lshlrev_b32_e32 v4, 2, v7
	v_lshl_add_u64 v[0:1], v[0:1], 0, s[0:1]
	v_and_b32_e32 v2, -16, v2
	v_and_b32_e32 v4, -16, v4
	v_lshl_add_u64 v[0:1], v[0:1], 0, v[160:161]
	v_ashrrev_i32_e32 v3, 31, v2
	v_ashrrev_i32_e32 v5, 31, v4
	v_lshl_add_u64 v[2:3], v[2:3], 3, v[0:1]
	v_lshl_add_u64 v[0:1], v[4:5], 3, v[0:1]
	global_load_dwordx2 v[2:3], v[2:3], off
	s_nop 0
	global_load_dwordx2 v[0:1], v[0:1], off
	v_and_b32_e32 v178, 15, v180
	v_lshlrev_b32_e32 v4, 2, v6
	v_lshl_or_b32 v4, v7, 9, v4
	v_add_u32_e32 v4, 0xfffff800, v4
	s_lshl_b32 s0, s6, 1
	v_and_b32_e32 v181, 48, v180
	v_add_u32_e32 v22, s45, v4
	v_add_u32_e32 v23, s49, v4
	v_lshlrev_b32_e32 v4, 2, v6
	v_mul_u32_u24_e32 v8, 0x110, v178
	v_add_u32_e32 v26, 0x200, v180
	s_ashr_i32 s1, s0, 31
	v_lshl_or_b32 v4, v7, 9, v4
	v_add3_u32 v183, s44, v181, v8
	s_ashr_i32 s20, s3, 6
	s_lshl_b32 s46, s12, 2
	v_ashrrev_i32_e32 v162, 10, v180
	v_add_u32_e32 v28, 0x600, v180
	v_ashrrev_i32_e32 v164, 10, v26
	s_lshl_b64 s[4:5], s[0:1], 4
	v_add_u32_e32 v24, s45, v4
	v_add_u32_e32 v25, s49, v4
	v_ashrrev_i32_e32 v163, 31, v162
	v_lshlrev_b32_e32 v5, 4, v26
	v_lshlrev_b32_e32 v6, 4, v28
	s_lshl_b32 s14, s20, 4
	v_ashrrev_i32_e32 v165, 31, v164
	s_or_b32 s4, s4, s46
	v_and_b32_e32 v14, 0x3f00, v5
	v_and_b32_e32 v16, 0x3f00, v6
	v_or_b32_e32 v179, s14, v178
	v_lshl_add_u64 v[4:5], s[4:5], 0, v[162:163]
	v_lshl_add_u64 v[6:7], s[4:5], 0, v[164:165]
	v_lshlrev_b32_e32 v18, 4, v180
	v_add_u32_e32 v27, 0x400, v180
	v_mul_lo_u32 v19, v179, s50
	v_lshlrev_b64 v[4:5], 14, v[4:5]
	v_lshlrev_b64 v[6:7], 14, v[6:7]
	v_mov_b32_e32 v15, v161
	v_ashrrev_i32_e32 v166, 10, v27
	v_ashrrev_i32_e32 v168, 10, v28
	v_add3_u32 v29, 0, v19, v181
	v_lshl_add_u64 v[4:5], s[34:35], 0, v[4:5]
	v_and_b32_e32 v160, 0x3f00, v18
	v_lshl_add_u64 v[6:7], s[34:35], 0, v[6:7]
	v_and_b32_e32 v12, 0xf0, v18
	v_ashrrev_i32_e32 v167, 31, v166
	v_ashrrev_i32_e32 v169, 31, v168
	v_lshl_add_u64 v[18:19], v[4:5], 0, v[160:161]
	v_lshl_add_u64 v[20:21], v[6:7], 0, v[14:15]
	v_lshl_add_u64 v[8:9], s[4:5], 0, v[166:167]
	v_lshl_add_u64 v[10:11], s[4:5], 0, v[168:169]
	v_lshlrev_b64 v[8:9], 14, v[8:9]
	v_lshlrev_b64 v[10:11], 14, v[10:11]
	v_mov_b32_e32 v17, v161
	v_lshl_add_u64 v[8:9], s[34:35], 0, v[8:9]
	v_lshl_add_u64 v[10:11], s[34:35], 0, v[10:11]
	v_mov_b32_e32 v13, v161
	v_lshl_add_u64 v[18:19], v[18:19], 0, v[12:13]
	v_lshl_add_u64 v[20:21], v[20:21], 0, v[12:13]
	v_lshlrev_b32_e32 v182, 3, v180
	s_mov_b32 s5, 0
	s_waitcnt vmcnt(1)
	v_log_f32_e32 v2, v2
	s_waitcnt vmcnt(0)
	v_log_f32_e32 v0, v0
	ds_write_b32 v22, v3
	v_sub_f32_e32 v2, v2, v3
	v_sub_f32_e32 v0, v0, v1
	ds_write_b32 v23, v2
	ds_write_b32 v24, v1
	ds_write_b32 v25, v0
	s_waitcnt lgkmcnt(0)
	s_barrier
	ds_read_b128 v[0:3], v183
	ds_read_b128 v[96:99], v29
	ds_read_b128 v[4:7], v183 offset:64
	v_lshl_add_u64 v[22:23], v[8:9], 0, v[160:161]
	v_lshl_add_u64 v[24:25], v[10:11], 0, v[16:17]
	ds_read_b128 v[100:103], v29 offset:64
	ds_read_b128 v[8:11], v183 offset:128
	s_waitcnt lgkmcnt(3)
	v_mfma_f32_16x16x32_bf16 v[0:3], v[0:3], v[96:99], 0
	v_lshl_add_u64 v[22:23], v[22:23], 0, v[12:13]
	v_lshl_add_u64 v[24:25], v[24:25], 0, v[12:13]
	ds_read_b128 v[104:107], v29 offset:128
	s_waitcnt lgkmcnt(2)
	v_mfma_f32_16x16x32_bf16 v[0:3], v[4:7], v[100:103], v[0:3]
	global_load_dwordx4 v[112:115], v[18:19], off
	global_load_dwordx4 v[116:119], v[20:21], off
	ds_read_b128 v[108:111], v29 offset:192
	ds_read_b128 v[4:7], v183 offset:192
	global_load_dwordx4 v[120:123], v[22:23], off
	global_load_dwordx4 v[124:127], v[24:25], off
	s_waitcnt lgkmcnt(2)
	v_mfma_f32_16x16x32_bf16 v[0:3], v[8:11], v[104:107], v[0:3]
	s_waitcnt lgkmcnt(0)
	v_mfma_f32_16x16x32_bf16 v[44:47], v[4:7], v[108:111], v[0:3]
	s_nop 5
	ds_read_b128 v[0:3], v183 offset:4352
	ds_read_b128 v[4:7], v183 offset:4416
	ds_read_b128 v[8:11], v183 offset:4480
	s_waitcnt lgkmcnt(2)
	v_mfma_f32_16x16x32_bf16 v[0:3], v[0:3], v[96:99], 0
	s_waitcnt lgkmcnt(1)
	v_mfma_f32_16x16x32_bf16 v[0:3], v[4:7], v[100:103], v[0:3]
	ds_read_b128 v[4:7], v183 offset:4544
	s_waitcnt lgkmcnt(1)
	v_mfma_f32_16x16x32_bf16 v[0:3], v[8:11], v[104:107], v[0:3]
	s_waitcnt lgkmcnt(0)
	v_mfma_f32_16x16x32_bf16 v[52:55], v[4:7], v[108:111], v[0:3]
	s_nop 5
	ds_read_b128 v[0:3], v183 offset:8704
	ds_read_b128 v[4:7], v183 offset:8768
	ds_read_b128 v[8:11], v183 offset:8832
	s_waitcnt lgkmcnt(2)
	v_mfma_f32_16x16x32_bf16 v[0:3], v[0:3], v[96:99], 0
	s_waitcnt lgkmcnt(1)
	v_mfma_f32_16x16x32_bf16 v[0:3], v[4:7], v[100:103], v[0:3]
	ds_read_b128 v[4:7], v183 offset:8896
	s_waitcnt lgkmcnt(1)
	v_mfma_f32_16x16x32_bf16 v[0:3], v[8:11], v[104:107], v[0:3]
	s_waitcnt lgkmcnt(0)
	v_mfma_f32_16x16x32_bf16 v[56:59], v[4:7], v[108:111], v[0:3]
	s_nop 5
	ds_read_b128 v[0:3], v183 offset:13056
	ds_read_b128 v[4:7], v183 offset:13120
	ds_read_b128 v[8:11], v183 offset:13184
	s_waitcnt lgkmcnt(2)
	v_mfma_f32_16x16x32_bf16 v[0:3], v[0:3], v[96:99], 0
	s_waitcnt lgkmcnt(1)
	v_mfma_f32_16x16x32_bf16 v[0:3], v[4:7], v[100:103], v[0:3]
	ds_read_b128 v[4:7], v183 offset:13248
	s_waitcnt lgkmcnt(1)
	v_mfma_f32_16x16x32_bf16 v[0:3], v[8:11], v[104:107], v[0:3]
	s_waitcnt lgkmcnt(0)
	v_mfma_f32_16x16x32_bf16 v[64:67], v[4:7], v[108:111], v[0:3]
	s_nop 5
	ds_read_b128 v[0:3], v183 offset:17408
	ds_read_b128 v[4:7], v183 offset:17472
	ds_read_b128 v[8:11], v183 offset:17536
	s_waitcnt lgkmcnt(2)
	v_mfma_f32_16x16x32_bf16 v[0:3], v[0:3], v[96:99], 0
	s_waitcnt lgkmcnt(1)
	v_mfma_f32_16x16x32_bf16 v[0:3], v[4:7], v[100:103], v[0:3]
	ds_read_b128 v[4:7], v183 offset:17600
	s_waitcnt lgkmcnt(1)
	v_mfma_f32_16x16x32_bf16 v[0:3], v[8:11], v[104:107], v[0:3]
	s_waitcnt lgkmcnt(0)
	v_mfma_f32_16x16x32_bf16 v[72:75], v[4:7], v[108:111], v[0:3]
	s_nop 5
	ds_read_b128 v[0:3], v183 offset:21760
	ds_read_b128 v[4:7], v183 offset:21824
	ds_read_b128 v[8:11], v183 offset:21888
	s_waitcnt lgkmcnt(2)
	v_mfma_f32_16x16x32_bf16 v[0:3], v[0:3], v[96:99], 0
	s_waitcnt lgkmcnt(1)
	v_mfma_f32_16x16x32_bf16 v[0:3], v[4:7], v[100:103], v[0:3]
	ds_read_b128 v[4:7], v183 offset:21952
	s_waitcnt lgkmcnt(1)
	v_mfma_f32_16x16x32_bf16 v[0:3], v[8:11], v[104:107], v[0:3]
	s_waitcnt lgkmcnt(0)
	v_mfma_f32_16x16x32_bf16 v[76:79], v[4:7], v[108:111], v[0:3]
	s_nop 5
	ds_read_b128 v[0:3], v183 offset:26112
	ds_read_b128 v[4:7], v183 offset:26176
	ds_read_b128 v[8:11], v183 offset:26240
	s_waitcnt lgkmcnt(2)
	v_mfma_f32_16x16x32_bf16 v[0:3], v[0:3], v[96:99], 0
	s_waitcnt lgkmcnt(1)
	v_mfma_f32_16x16x32_bf16 v[0:3], v[4:7], v[100:103], v[0:3]
	ds_read_b128 v[4:7], v183 offset:26304
	s_waitcnt lgkmcnt(1)
	v_mfma_f32_16x16x32_bf16 v[0:3], v[8:11], v[104:107], v[0:3]
	s_waitcnt lgkmcnt(0)
	v_mfma_f32_16x16x32_bf16 v[84:87], v[4:7], v[108:111], v[0:3]
	s_nop 5
	ds_read_b128 v[0:3], v183 offset:30464
	ds_read_b128 v[4:7], v183 offset:30528
	ds_read_b128 v[8:11], v183 offset:30592
	s_waitcnt lgkmcnt(2)
	v_mfma_f32_16x16x32_bf16 v[0:3], v[0:3], v[96:99], 0
	s_waitcnt lgkmcnt(1)
	v_mfma_f32_16x16x32_bf16 v[0:3], v[4:7], v[100:103], v[0:3]
	ds_read_b128 v[4:7], v183 offset:30656
	s_waitcnt lgkmcnt(1)
	v_mfma_f32_16x16x32_bf16 v[0:3], v[8:11], v[104:107], v[0:3]
	s_waitcnt lgkmcnt(0)
	v_mfma_f32_16x16x32_bf16 v[88:91], v[4:7], v[108:111], v[0:3]
	s_nop 5
	v_lshrrev_b32_e32 v0, 4, v180
	v_mul_lo_u32 v3, v0, s50
	v_lshrrev_b32_e32 v0, 4, v26
	v_mul_lo_u32 v4, v0, s50
	v_lshrrev_b32_e32 v0, 4, v27
	v_mul_lo_u32 v5, v0, s50
	v_lshrrev_b32_e32 v0, 4, v28
	v_mul_lo_u32 v6, v0, s50
	v_lshl_add_u64 v[0:1], s[34:35], 0, v[160:161]
	s_and_b32 s1, s3, 0xffffffc0
	v_lshl_add_u64 v[170:171], v[0:1], 0, v[12:13]
	v_lshl_add_u64 v[0:1], s[34:35], 0, v[14:15]
	v_add_u32_e32 v2, s44, v12
	s_add_i32 s1, s45, s1
	v_lshl_add_u64 v[172:173], v[0:1], 0, v[12:13]
	v_lshl_add_u64 v[0:1], s[34:35], 0, v[16:17]
	v_mov_b32_e32 v24, 0
	v_lshl_add_u32 v184, v178, 2, s1
	s_or_b32 s4, s46, 2
	v_lshl_add_u64 v[174:175], v[0:1], 0, v[12:13]
	s_mov_b64 s[6:7], -1
	s_mov_b64 s[8:9], 0
	v_add_u32_e32 v160, v2, v3
	v_add_u32_e32 v185, v2, v4
	v_add_u32_e32 v186, v2, v5
	v_add_u32_e32 v187, v2, v6
	s_mov_b32 s1, s5
	v_mov_b32_e32 v25, v24
	v_mov_b32_e32 v26, v24
	v_mov_b32_e32 v27, v24
	v_mov_b32_e32 v36, v24
	v_mov_b32_e32 v37, v24
	v_mov_b32_e32 v38, v24
	v_mov_b32_e32 v39, v24
	v_mov_b32_e32 v40, v24
	v_mov_b32_e32 v41, v24
	v_mov_b32_e32 v42, v24
	v_mov_b32_e32 v43, v24
	v_mov_b32_e32 v48, v24
	v_mov_b32_e32 v49, v24
	v_mov_b32_e32 v50, v24
	v_mov_b32_e32 v51, v24
	v_mov_b32_e32 v60, v24
	v_mov_b32_e32 v61, v24
	v_mov_b32_e32 v62, v24
	v_mov_b32_e32 v63, v24
	v_mov_b32_e32 v68, v24
	v_mov_b32_e32 v69, v24
	v_mov_b32_e32 v70, v24
	v_mov_b32_e32 v71, v24
	v_mov_b32_e32 v80, v24
	v_mov_b32_e32 v81, v24
	v_mov_b32_e32 v82, v24
	v_mov_b32_e32 v83, v24
	v_mov_b32_e32 v92, v24
	v_mov_b32_e32 v93, v24
	v_mov_b32_e32 v94, v24
	v_mov_b32_e32 v95, v24
	v_mov_b32_e32 v32, v24
	v_mov_b32_e32 v33, v24
	v_mov_b32_e32 v34, v24
	v_mov_b32_e32 v35, v24
	v_mov_b32_e32 v28, v24
	v_mov_b32_e32 v29, v24
	v_mov_b32_e32 v30, v24
	v_mov_b32_e32 v31, v24
	v_mov_b32_e32 v20, v24
	v_mov_b32_e32 v21, v24
	v_mov_b32_e32 v22, v24
	v_mov_b32_e32 v23, v24
	v_mov_b32_e32 v16, v24
	v_mov_b32_e32 v17, v24
	v_mov_b32_e32 v18, v24
	v_mov_b32_e32 v19, v24
	v_mov_b32_e32 v12, v24
	v_mov_b32_e32 v13, v24
	v_mov_b32_e32 v14, v24
	v_mov_b32_e32 v15, v24
	v_mov_b32_e32 v8, v24
	v_mov_b32_e32 v9, v24
	v_mov_b32_e32 v10, v24
	v_mov_b32_e32 v11, v24
	v_mov_b32_e32 v4, v24
	v_mov_b32_e32 v5, v24
	v_mov_b32_e32 v6, v24
	v_mov_b32_e32 v7, v24
	v_mov_b32_e32 v0, v24
	v_mov_b32_e32 v1, v24
	v_mov_b32_e32 v2, v24
	v_mov_b32_e32 v3, v24
	s_barrier
	s_branch .LBB0_852
